# phase0 mod_partials: all 64 row loads of a half issued up front (64 in flight instead of 16)
# baseline (speedup 1.0000x reference)
.LBB0_21:
	global_load_dword v132, v[12:13], off nt
	v_add_co_u32_e32 v12, vcc, 0x3000, v12
	s_nop 1
	v_addc_co_u32_e32 v13, vcc, 0, v13, vcc
	global_load_dword v133, v[12:13], off nt
	v_add_co_u32_e32 v12, vcc, 0x3000, v12
	s_nop 1
	v_addc_co_u32_e32 v13, vcc, 0, v13, vcc
	global_load_dword v134, v[12:13], off nt
	v_add_co_u32_e32 v12, vcc, 0x3000, v12
	s_nop 1
	v_addc_co_u32_e32 v13, vcc, 0, v13, vcc
	global_load_dword v135, v[12:13], off nt
	v_add_co_u32_e32 v12, vcc, 0x3000, v12
	s_nop 1
	v_addc_co_u32_e32 v13, vcc, 0, v13, vcc
	global_load_dword v136, v[12:13], off nt
	v_add_co_u32_e32 v12, vcc, 0x3000, v12
	s_nop 1
	v_addc_co_u32_e32 v13, vcc, 0, v13, vcc
	global_load_dword v137, v[12:13], off nt
	v_add_co_u32_e32 v12, vcc, 0x3000, v12
	s_nop 1
	v_addc_co_u32_e32 v13, vcc, 0, v13, vcc
	global_load_dword v138, v[12:13], off nt
	v_add_co_u32_e32 v12, vcc, 0x3000, v12
	s_nop 1
	v_addc_co_u32_e32 v13, vcc, 0, v13, vcc
	global_load_dword v139, v[12:13], off nt
	v_add_co_u32_e32 v12, vcc, 0x3000, v12
	s_nop 1
	v_addc_co_u32_e32 v13, vcc, 0, v13, vcc
	global_load_dword v140, v[12:13], off nt
	v_add_co_u32_e32 v12, vcc, 0x3000, v12
	s_nop 1
	v_addc_co_u32_e32 v13, vcc, 0, v13, vcc
	global_load_dword v141, v[12:13], off nt
	v_add_co_u32_e32 v12, vcc, 0x3000, v12
	s_nop 1
	v_addc_co_u32_e32 v13, vcc, 0, v13, vcc
	global_load_dword v142, v[12:13], off nt
	v_add_co_u32_e32 v12, vcc, 0x3000, v12
	s_nop 1
	v_addc_co_u32_e32 v13, vcc, 0, v13, vcc
	global_load_dword v143, v[12:13], off nt
	v_add_co_u32_e32 v12, vcc, 0x3000, v12
	s_nop 1
	v_addc_co_u32_e32 v13, vcc, 0, v13, vcc
	global_load_dword v144, v[12:13], off nt
	v_add_co_u32_e32 v12, vcc, 0x3000, v12
	s_nop 1
	v_addc_co_u32_e32 v13, vcc, 0, v13, vcc
	global_load_dword v145, v[12:13], off nt
	v_add_co_u32_e32 v12, vcc, 0x3000, v12
	s_nop 1
	v_addc_co_u32_e32 v13, vcc, 0, v13, vcc
	global_load_dword v146, v[12:13], off nt
	v_add_co_u32_e32 v12, vcc, 0x3000, v12
	s_nop 1
	v_addc_co_u32_e32 v13, vcc, 0, v13, vcc
	global_load_dword v147, v[12:13], off nt
	v_add_co_u32_e32 v12, vcc, 0x3000, v12
	s_nop 1
	v_addc_co_u32_e32 v13, vcc, 0, v13, vcc
	global_load_dword v148, v[12:13], off nt
	v_add_co_u32_e32 v12, vcc, 0x3000, v12
	s_nop 1
	v_addc_co_u32_e32 v13, vcc, 0, v13, vcc
	global_load_dword v149, v[12:13], off nt
	v_add_co_u32_e32 v12, vcc, 0x3000, v12
	s_nop 1
	v_addc_co_u32_e32 v13, vcc, 0, v13, vcc
	global_load_dword v150, v[12:13], off nt
	v_add_co_u32_e32 v12, vcc, 0x3000, v12
	s_nop 1
	v_addc_co_u32_e32 v13, vcc, 0, v13, vcc
	global_load_dword v151, v[12:13], off nt
	v_add_co_u32_e32 v12, vcc, 0x3000, v12
	s_nop 1
	v_addc_co_u32_e32 v13, vcc, 0, v13, vcc
	global_load_dword v152, v[12:13], off nt
	v_add_co_u32_e32 v12, vcc, 0x3000, v12
	s_nop 1
	v_addc_co_u32_e32 v13, vcc, 0, v13, vcc
	global_load_dword v153, v[12:13], off nt
	v_add_co_u32_e32 v12, vcc, 0x3000, v12
	s_nop 1
	v_addc_co_u32_e32 v13, vcc, 0, v13, vcc
	global_load_dword v154, v[12:13], off nt
	v_add_co_u32_e32 v12, vcc, 0x3000, v12
	s_nop 1
	v_addc_co_u32_e32 v13, vcc, 0, v13, vcc
	global_load_dword v155, v[12:13], off nt
	v_add_co_u32_e32 v12, vcc, 0x3000, v12
	s_nop 1
	v_addc_co_u32_e32 v13, vcc, 0, v13, vcc
	global_load_dword v156, v[12:13], off nt
	v_add_co_u32_e32 v12, vcc, 0x3000, v12
	s_nop 1
	v_addc_co_u32_e32 v13, vcc, 0, v13, vcc
	global_load_dword v157, v[12:13], off nt
	v_add_co_u32_e32 v12, vcc, 0x3000, v12
	s_nop 1
	v_addc_co_u32_e32 v13, vcc, 0, v13, vcc
	global_load_dword v158, v[12:13], off nt
	v_add_co_u32_e32 v12, vcc, 0x3000, v12
	s_nop 1
	v_addc_co_u32_e32 v13, vcc, 0, v13, vcc
	global_load_dword v159, v[12:13], off nt
	v_add_co_u32_e32 v12, vcc, 0x3000, v12
	s_nop 1
	v_addc_co_u32_e32 v13, vcc, 0, v13, vcc
	global_load_dword v160, v[12:13], off nt
	v_add_co_u32_e32 v12, vcc, 0x3000, v12
	s_nop 1
	v_addc_co_u32_e32 v13, vcc, 0, v13, vcc
	global_load_dword v161, v[12:13], off nt
	v_add_co_u32_e32 v12, vcc, 0x3000, v12
	s_nop 1
	v_addc_co_u32_e32 v13, vcc, 0, v13, vcc
	global_load_dword v162, v[12:13], off nt
	v_add_co_u32_e32 v12, vcc, 0x3000, v12
	s_nop 1
	v_addc_co_u32_e32 v13, vcc, 0, v13, vcc
	global_load_dword v163, v[12:13], off nt
	v_add_co_u32_e32 v12, vcc, 0x3000, v12
	s_nop 1
	v_addc_co_u32_e32 v13, vcc, 0, v13, vcc
	global_load_dword v164, v[12:13], off nt
	v_add_co_u32_e32 v12, vcc, 0x3000, v12
	s_nop 1
	v_addc_co_u32_e32 v13, vcc, 0, v13, vcc
	global_load_dword v165, v[12:13], off nt
	v_add_co_u32_e32 v12, vcc, 0x3000, v12
	s_nop 1
	v_addc_co_u32_e32 v13, vcc, 0, v13, vcc
	global_load_dword v166, v[12:13], off nt
	v_add_co_u32_e32 v12, vcc, 0x3000, v12
	s_nop 1
	v_addc_co_u32_e32 v13, vcc, 0, v13, vcc
	global_load_dword v167, v[12:13], off nt
	v_add_co_u32_e32 v12, vcc, 0x3000, v12
	s_nop 1
	v_addc_co_u32_e32 v13, vcc, 0, v13, vcc
	global_load_dword v168, v[12:13], off nt
	v_add_co_u32_e32 v12, vcc, 0x3000, v12
	s_nop 1
	v_addc_co_u32_e32 v13, vcc, 0, v13, vcc
	global_load_dword v169, v[12:13], off nt
	v_add_co_u32_e32 v12, vcc, 0x3000, v12
	s_nop 1
	v_addc_co_u32_e32 v13, vcc, 0, v13, vcc
	global_load_dword v170, v[12:13], off nt
	v_add_co_u32_e32 v12, vcc, 0x3000, v12
	s_nop 1
	v_addc_co_u32_e32 v13, vcc, 0, v13, vcc
	global_load_dword v171, v[12:13], off nt
	v_add_co_u32_e32 v12, vcc, 0x3000, v12
	s_nop 1
	v_addc_co_u32_e32 v13, vcc, 0, v13, vcc
	global_load_dword v172, v[12:13], off nt
	v_add_co_u32_e32 v12, vcc, 0x3000, v12
	s_nop 1
	v_addc_co_u32_e32 v13, vcc, 0, v13, vcc
	global_load_dword v173, v[12:13], off nt
	v_add_co_u32_e32 v12, vcc, 0x3000, v12
	s_nop 1
	v_addc_co_u32_e32 v13, vcc, 0, v13, vcc
	global_load_dword v174, v[12:13], off nt
	v_add_co_u32_e32 v12, vcc, 0x3000, v12
	s_nop 1
	v_addc_co_u32_e32 v13, vcc, 0, v13, vcc
	global_load_dword v175, v[12:13], off nt
	v_add_co_u32_e32 v12, vcc, 0x3000, v12
	s_nop 1
	v_addc_co_u32_e32 v13, vcc, 0, v13, vcc
	global_load_dword v176, v[12:13], off nt
	v_add_co_u32_e32 v12, vcc, 0x3000, v12
	s_nop 1
	v_addc_co_u32_e32 v13, vcc, 0, v13, vcc
	global_load_dword v177, v[12:13], off nt
	v_add_co_u32_e32 v12, vcc, 0x3000, v12
	s_nop 1
	v_addc_co_u32_e32 v13, vcc, 0, v13, vcc
	global_load_dword v178, v[12:13], off nt
	v_add_co_u32_e32 v12, vcc, 0x3000, v12
	s_nop 1
	v_addc_co_u32_e32 v13, vcc, 0, v13, vcc
	global_load_dword v179, v[12:13], off nt
	v_add_co_u32_e32 v12, vcc, 0x3000, v12
	s_nop 1
	v_addc_co_u32_e32 v13, vcc, 0, v13, vcc
	global_load_dword v180, v[12:13], off nt
	v_add_co_u32_e32 v12, vcc, 0x3000, v12
	s_nop 1
	v_addc_co_u32_e32 v13, vcc, 0, v13, vcc
	global_load_dword v181, v[12:13], off nt
	v_add_co_u32_e32 v12, vcc, 0x3000, v12
	s_nop 1
	v_addc_co_u32_e32 v13, vcc, 0, v13, vcc
	global_load_dword v182, v[12:13], off nt
	v_add_co_u32_e32 v12, vcc, 0x3000, v12
	s_nop 1
	v_addc_co_u32_e32 v13, vcc, 0, v13, vcc
	global_load_dword v183, v[12:13], off nt
	v_add_co_u32_e32 v12, vcc, 0x3000, v12
	s_nop 1
	v_addc_co_u32_e32 v13, vcc, 0, v13, vcc
	global_load_dword v184, v[12:13], off nt
	v_add_co_u32_e32 v12, vcc, 0x3000, v12
	s_nop 1
	v_addc_co_u32_e32 v13, vcc, 0, v13, vcc
	global_load_dword v185, v[12:13], off nt
	v_add_co_u32_e32 v12, vcc, 0x3000, v12
	s_nop 1
	v_addc_co_u32_e32 v13, vcc, 0, v13, vcc
	global_load_dword v186, v[12:13], off nt
	v_add_co_u32_e32 v12, vcc, 0x3000, v12
	s_nop 1
	v_addc_co_u32_e32 v13, vcc, 0, v13, vcc
	global_load_dword v187, v[12:13], off nt
	v_add_co_u32_e32 v12, vcc, 0x3000, v12
	s_nop 1
	v_addc_co_u32_e32 v13, vcc, 0, v13, vcc
	global_load_dword v188, v[12:13], off nt
	v_add_co_u32_e32 v12, vcc, 0x3000, v12
	s_nop 1
	v_addc_co_u32_e32 v13, vcc, 0, v13, vcc
	global_load_dword v189, v[12:13], off nt
	v_add_co_u32_e32 v12, vcc, 0x3000, v12
	s_nop 1
	v_addc_co_u32_e32 v13, vcc, 0, v13, vcc
	global_load_dword v190, v[12:13], off nt
	v_add_co_u32_e32 v12, vcc, 0x3000, v12
	s_nop 1
	v_addc_co_u32_e32 v13, vcc, 0, v13, vcc
	global_load_dword v191, v[12:13], off nt
	v_add_co_u32_e32 v12, vcc, 0x3000, v12
	s_nop 1
	v_addc_co_u32_e32 v13, vcc, 0, v13, vcc
	global_load_dword v192, v[12:13], off nt
	v_add_co_u32_e32 v12, vcc, 0x3000, v12
	s_nop 1
	v_addc_co_u32_e32 v13, vcc, 0, v13, vcc
	global_load_dword v193, v[12:13], off nt
	v_add_co_u32_e32 v12, vcc, 0x3000, v12
	s_nop 1
	v_addc_co_u32_e32 v13, vcc, 0, v13, vcc
	global_load_dword v194, v[12:13], off nt
	v_add_co_u32_e32 v12, vcc, 0x3000, v12
	s_nop 1
	v_addc_co_u32_e32 v13, vcc, 0, v13, vcc
	global_load_dword v195, v[12:13], off nt
	v_subrev_u32_e32 v44, 56, v27
	ds_bpermute_b32 v40, v44, v0
	ds_bpermute_b32 v41, v44, v23
	ds_bpermute_b32 v42, v44, v24
	ds_bpermute_b32 v43, v44, v25
	ds_bpermute_b32 v124, v44, v26
	v_subrev_u32_e32 v50, 52, v27
	ds_bpermute_b32 v46, v50, v0
	ds_bpermute_b32 v47, v50, v23
	ds_bpermute_b32 v48, v50, v24
	ds_bpermute_b32 v49, v50, v25
	ds_bpermute_b32 v125, v50, v26
	v_subrev_u32_e32 v56, 48, v27
	ds_bpermute_b32 v52, v56, v0
	ds_bpermute_b32 v53, v56, v23
	ds_bpermute_b32 v54, v56, v24
	ds_bpermute_b32 v55, v56, v25
	ds_bpermute_b32 v126, v56, v26
	v_subrev_u32_e32 v33, 60, v27
	v_subrev_u32_e32 v106, 20, v27
	ds_bpermute_b32 v34, v33, v0
	ds_bpermute_b32 v35, v33, v23
	ds_bpermute_b32 v36, v33, v24
	ds_bpermute_b32 v37, v33, v25
	ds_bpermute_b32 v33, v33, v26
	v_add_u32_e32 v110, -16, v27
	v_add_u32_e32 v114, -12, v27
	v_subrev_u32_e32 v68, 44, v27
	v_add_u32_e32 v118, -8, v27
	ds_bpermute_b32 v39, v106, v26
	ds_bpermute_b32 v45, v110, v26
	ds_bpermute_b32 v51, v114, v26
	v_subrev_u32_e32 v86, 40, v27
	v_add_u32_e32 v122, -4, v27
	ds_bpermute_b32 v64, v68, v0
	ds_bpermute_b32 v65, v68, v23
	ds_bpermute_b32 v66, v68, v24
	ds_bpermute_b32 v67, v68, v25
	ds_bpermute_b32 v127, v68, v26
	ds_bpermute_b32 v57, v118, v26
	v_subrev_u32_e32 v90, 36, v27
	ds_bpermute_b32 v68, v86, v0
	ds_bpermute_b32 v69, v86, v23
	ds_bpermute_b32 v84, v86, v24
	ds_bpermute_b32 v85, v86, v25
	ds_bpermute_b32 v128, v86, v26
	ds_bpermute_b32 v59, v122, v26
	v_subrev_u32_e32 v94, 32, v27
	ds_bpermute_b32 v86, v90, v0
	ds_bpermute_b32 v87, v90, v23
	s_waitcnt vmcnt(63) lgkmcnt(14)
	v_pk_fma_f32 v[10:11], v[132:133], v[34:35], v[10:11] op_sel_hi:[0,1,1]
	v_pk_fma_f32 v[8:9], v[132:133], v[36:37], v[8:9] op_sel_hi:[0,1,1]
	v_fmac_f32_e32 v22, v132, v33
	ds_bpermute_b32 v88, v90, v24
	ds_bpermute_b32 v89, v90, v25
	ds_bpermute_b32 v129, v90, v26
	v_subrev_u32_e32 v98, 28, v27
	ds_bpermute_b32 v90, v94, v0
	ds_bpermute_b32 v91, v94, v23
	ds_bpermute_b32 v92, v94, v24
	ds_bpermute_b32 v93, v94, v25
	ds_bpermute_b32 v130, v94, v26
	v_subrev_u32_e32 v102, 24, v27
	ds_bpermute_b32 v94, v98, v0
	ds_bpermute_b32 v95, v98, v23
	ds_bpermute_b32 v96, v98, v24
	ds_bpermute_b32 v97, v98, v25
	ds_bpermute_b32 v131, v98, v26
	ds_bpermute_b32 v98, v102, v0
	ds_bpermute_b32 v99, v102, v23
	ds_bpermute_b32 v100, v102, v24
	ds_bpermute_b32 v101, v102, v25
	ds_bpermute_b32 v15, v102, v26
	ds_bpermute_b32 v102, v106, v0
	ds_bpermute_b32 v103, v106, v23
	ds_bpermute_b32 v104, v106, v24
	ds_bpermute_b32 v105, v106, v25
	ds_bpermute_b32 v106, v110, v0
	ds_bpermute_b32 v107, v110, v23
	ds_bpermute_b32 v108, v110, v24
	ds_bpermute_b32 v109, v110, v25
	ds_bpermute_b32 v110, v114, v0
	ds_bpermute_b32 v111, v114, v23
	ds_bpermute_b32 v112, v114, v24
	ds_bpermute_b32 v113, v114, v25
	ds_bpermute_b32 v114, v118, v0
	ds_bpermute_b32 v115, v118, v23
	ds_bpermute_b32 v116, v118, v24
	ds_bpermute_b32 v117, v118, v25
	ds_bpermute_b32 v118, v122, v0
	ds_bpermute_b32 v119, v122, v23
	ds_bpermute_b32 v120, v122, v24
	ds_bpermute_b32 v121, v122, v25
	ds_bpermute_b32 v28, v27, v0
	s_waitcnt vmcnt(62)
	v_pk_fma_f32 v[10:11], v[132:133], v[40:41], v[10:11] op_sel:[1,0,0] op_sel_hi:[1,1,1]
	v_pk_fma_f32 v[8:9], v[132:133], v[42:43], v[8:9] op_sel:[1,0,0] op_sel_hi:[1,1,1]
	v_fmac_f32_e32 v22, v133, v124
	s_waitcnt vmcnt(61)
	v_pk_fma_f32 v[10:11], v[134:135], v[46:47], v[10:11] op_sel_hi:[0,1,1]
	v_pk_fma_f32 v[8:9], v[134:135], v[48:49], v[8:9] op_sel_hi:[0,1,1]
	v_fmac_f32_e32 v22, v134, v125
	s_waitcnt vmcnt(60)
	v_pk_fma_f32 v[10:11], v[134:135], v[52:53], v[10:11] op_sel:[1,0,0] op_sel_hi:[1,1,1]
	v_pk_fma_f32 v[8:9], v[134:135], v[54:55], v[8:9] op_sel:[1,0,0] op_sel_hi:[1,1,1]
	v_fmac_f32_e32 v22, v135, v126
	s_waitcnt vmcnt(59) lgkmcnt(14)
	v_pk_fma_f32 v[10:11], v[136:137], v[64:65], v[10:11] op_sel_hi:[0,1,1]
	v_pk_fma_f32 v[8:9], v[136:137], v[66:67], v[8:9] op_sel_hi:[0,1,1]
	v_fmac_f32_e32 v22, v136, v127
	s_waitcnt vmcnt(58)
	v_pk_fma_f32 v[10:11], v[136:137], v[68:69], v[10:11] op_sel:[1,0,0] op_sel_hi:[1,1,1]
	v_pk_fma_f32 v[8:9], v[136:137], v[84:85], v[8:9] op_sel:[1,0,0] op_sel_hi:[1,1,1]
	v_fmac_f32_e32 v22, v137, v128
	s_waitcnt vmcnt(57)
	v_pk_fma_f32 v[10:11], v[138:139], v[86:87], v[10:11] op_sel_hi:[0,1,1]
	v_pk_fma_f32 v[8:9], v[138:139], v[88:89], v[8:9] op_sel_hi:[0,1,1]
	v_fmac_f32_e32 v22, v138, v129
	s_waitcnt vmcnt(56)
	v_pk_fma_f32 v[10:11], v[138:139], v[90:91], v[10:11] op_sel:[1,0,0] op_sel_hi:[1,1,1]
	v_pk_fma_f32 v[8:9], v[138:139], v[92:93], v[8:9] op_sel:[1,0,0] op_sel_hi:[1,1,1]
	v_fmac_f32_e32 v22, v139, v130
	s_waitcnt vmcnt(55)
	v_pk_fma_f32 v[10:11], v[140:141], v[94:95], v[10:11] op_sel_hi:[0,1,1]
	v_pk_fma_f32 v[8:9], v[140:141], v[96:97], v[8:9] op_sel_hi:[0,1,1]
	v_fmac_f32_e32 v22, v140, v131
	s_waitcnt vmcnt(54)
	v_pk_fma_f32 v[10:11], v[140:141], v[98:99], v[10:11] op_sel:[1,0,0] op_sel_hi:[1,1,1]
	v_pk_fma_f32 v[8:9], v[140:141], v[100:101], v[8:9] op_sel:[1,0,0] op_sel_hi:[1,1,1]
	v_fmac_f32_e32 v22, v141, v15
	ds_bpermute_b32 v29, v27, v23
	ds_bpermute_b32 v30, v27, v24
	ds_bpermute_b32 v31, v27, v25
	ds_bpermute_b32 v123, v27, v26
	s_waitcnt vmcnt(53)
	v_pk_fma_f32 v[10:11], v[142:143], v[102:103], v[10:11] op_sel_hi:[0,1,1]
	v_pk_fma_f32 v[8:9], v[142:143], v[104:105], v[8:9] op_sel_hi:[0,1,1]
	v_fmac_f32_e32 v22, v142, v39
	s_waitcnt vmcnt(52)
	v_pk_fma_f32 v[10:11], v[142:143], v[106:107], v[10:11] op_sel:[1,0,0] op_sel_hi:[1,1,1]
	s_waitcnt lgkmcnt(14)
	v_pk_fma_f32 v[8:9], v[142:143], v[108:109], v[8:9] op_sel:[1,0,0] op_sel_hi:[1,1,1]
	v_fmac_f32_e32 v22, v143, v45
	s_waitcnt vmcnt(51)
	v_pk_fma_f32 v[10:11], v[144:145], v[110:111], v[10:11] op_sel_hi:[0,1,1]
	s_waitcnt lgkmcnt(13)
	v_pk_fma_f32 v[8:9], v[144:145], v[112:113], v[8:9] op_sel_hi:[0,1,1]
	v_fmac_f32_e32 v22, v144, v51
	s_waitcnt vmcnt(50) lgkmcnt(11)
	v_pk_fma_f32 v[10:11], v[144:145], v[114:115], v[10:11] op_sel:[1,0,0] op_sel_hi:[1,1,1]
	s_waitcnt lgkmcnt(9)
	v_pk_fma_f32 v[8:9], v[144:145], v[116:117], v[8:9] op_sel:[1,0,0] op_sel_hi:[1,1,1]
	v_fmac_f32_e32 v22, v145, v57
	s_waitcnt vmcnt(49) lgkmcnt(7)
	v_pk_fma_f32 v[10:11], v[146:147], v[118:119], v[10:11] op_sel_hi:[0,1,1]
	s_waitcnt lgkmcnt(5)
	v_pk_fma_f32 v[8:9], v[146:147], v[120:121], v[8:9] op_sel_hi:[0,1,1]
	v_fmac_f32_e32 v22, v146, v59
	v_add_u32_e32 v27, 64, v27
	s_waitcnt vmcnt(48) lgkmcnt(3)
	v_pk_fma_f32 v[10:11], v[146:147], v[28:29], v[10:11] op_sel:[1,0,0] op_sel_hi:[1,1,1]
	s_waitcnt lgkmcnt(1)
	v_pk_fma_f32 v[8:9], v[146:147], v[30:31], v[8:9] op_sel:[1,0,0] op_sel_hi:[1,1,1]
	s_waitcnt lgkmcnt(0)
	v_fmac_f32_e32 v22, v147, v123
	v_subrev_u32_e32 v44, 56, v27
	ds_bpermute_b32 v40, v44, v0
	ds_bpermute_b32 v41, v44, v23
	ds_bpermute_b32 v42, v44, v24
	ds_bpermute_b32 v43, v44, v25
	ds_bpermute_b32 v124, v44, v26
	v_subrev_u32_e32 v50, 52, v27
	ds_bpermute_b32 v46, v50, v0
	ds_bpermute_b32 v47, v50, v23
	ds_bpermute_b32 v48, v50, v24
	ds_bpermute_b32 v49, v50, v25
	ds_bpermute_b32 v125, v50, v26
	v_subrev_u32_e32 v56, 48, v27
	ds_bpermute_b32 v52, v56, v0
	ds_bpermute_b32 v53, v56, v23
	ds_bpermute_b32 v54, v56, v24
	ds_bpermute_b32 v55, v56, v25
	ds_bpermute_b32 v126, v56, v26
	v_subrev_u32_e32 v33, 60, v27
	v_subrev_u32_e32 v106, 20, v27
	ds_bpermute_b32 v34, v33, v0
	ds_bpermute_b32 v35, v33, v23
	ds_bpermute_b32 v36, v33, v24
	ds_bpermute_b32 v37, v33, v25
	ds_bpermute_b32 v33, v33, v26
	v_add_u32_e32 v110, -16, v27
	v_add_u32_e32 v114, -12, v27
	v_subrev_u32_e32 v68, 44, v27
	v_add_u32_e32 v118, -8, v27
	ds_bpermute_b32 v39, v106, v26
	ds_bpermute_b32 v45, v110, v26
	ds_bpermute_b32 v51, v114, v26
	v_subrev_u32_e32 v86, 40, v27
	v_add_u32_e32 v122, -4, v27
	ds_bpermute_b32 v64, v68, v0
	ds_bpermute_b32 v65, v68, v23
	ds_bpermute_b32 v66, v68, v24
	ds_bpermute_b32 v67, v68, v25
	ds_bpermute_b32 v127, v68, v26
	ds_bpermute_b32 v57, v118, v26
	v_subrev_u32_e32 v90, 36, v27
	ds_bpermute_b32 v68, v86, v0
	ds_bpermute_b32 v69, v86, v23
	ds_bpermute_b32 v84, v86, v24
	ds_bpermute_b32 v85, v86, v25
	ds_bpermute_b32 v128, v86, v26
	ds_bpermute_b32 v59, v122, v26
	v_subrev_u32_e32 v94, 32, v27
	ds_bpermute_b32 v86, v90, v0
	ds_bpermute_b32 v87, v90, v23
	s_waitcnt vmcnt(47) lgkmcnt(14)
	v_pk_fma_f32 v[10:11], v[148:149], v[34:35], v[10:11] op_sel_hi:[0,1,1]
	v_pk_fma_f32 v[8:9], v[148:149], v[36:37], v[8:9] op_sel_hi:[0,1,1]
	v_fmac_f32_e32 v22, v148, v33
	ds_bpermute_b32 v88, v90, v24
	ds_bpermute_b32 v89, v90, v25
	ds_bpermute_b32 v129, v90, v26
	v_subrev_u32_e32 v98, 28, v27
	ds_bpermute_b32 v90, v94, v0
	ds_bpermute_b32 v91, v94, v23
	ds_bpermute_b32 v92, v94, v24
	ds_bpermute_b32 v93, v94, v25
	ds_bpermute_b32 v130, v94, v26
	v_subrev_u32_e32 v102, 24, v27
	ds_bpermute_b32 v94, v98, v0
	ds_bpermute_b32 v95, v98, v23
	ds_bpermute_b32 v96, v98, v24
	ds_bpermute_b32 v97, v98, v25
	ds_bpermute_b32 v131, v98, v26
	ds_bpermute_b32 v98, v102, v0
	ds_bpermute_b32 v99, v102, v23
	ds_bpermute_b32 v100, v102, v24
	ds_bpermute_b32 v101, v102, v25
	ds_bpermute_b32 v15, v102, v26
	ds_bpermute_b32 v102, v106, v0
	ds_bpermute_b32 v103, v106, v23
	ds_bpermute_b32 v104, v106, v24
	ds_bpermute_b32 v105, v106, v25
	ds_bpermute_b32 v106, v110, v0
	ds_bpermute_b32 v107, v110, v23
	ds_bpermute_b32 v108, v110, v24
	ds_bpermute_b32 v109, v110, v25
	ds_bpermute_b32 v110, v114, v0
	ds_bpermute_b32 v111, v114, v23
	ds_bpermute_b32 v112, v114, v24
	ds_bpermute_b32 v113, v114, v25
	ds_bpermute_b32 v114, v118, v0
	ds_bpermute_b32 v115, v118, v23
	ds_bpermute_b32 v116, v118, v24
	ds_bpermute_b32 v117, v118, v25
	ds_bpermute_b32 v118, v122, v0
	ds_bpermute_b32 v119, v122, v23
	ds_bpermute_b32 v120, v122, v24
	ds_bpermute_b32 v121, v122, v25
	ds_bpermute_b32 v28, v27, v0
	s_waitcnt vmcnt(46)
	v_pk_fma_f32 v[10:11], v[148:149], v[40:41], v[10:11] op_sel:[1,0,0] op_sel_hi:[1,1,1]
	v_pk_fma_f32 v[8:9], v[148:149], v[42:43], v[8:9] op_sel:[1,0,0] op_sel_hi:[1,1,1]
	v_fmac_f32_e32 v22, v149, v124
	s_waitcnt vmcnt(45)
	v_pk_fma_f32 v[10:11], v[150:151], v[46:47], v[10:11] op_sel_hi:[0,1,1]
	v_pk_fma_f32 v[8:9], v[150:151], v[48:49], v[8:9] op_sel_hi:[0,1,1]
	v_fmac_f32_e32 v22, v150, v125
	s_waitcnt vmcnt(44)
	v_pk_fma_f32 v[10:11], v[150:151], v[52:53], v[10:11] op_sel:[1,0,0] op_sel_hi:[1,1,1]
	v_pk_fma_f32 v[8:9], v[150:151], v[54:55], v[8:9] op_sel:[1,0,0] op_sel_hi:[1,1,1]
	v_fmac_f32_e32 v22, v151, v126
	s_waitcnt vmcnt(43) lgkmcnt(14)
	v_pk_fma_f32 v[10:11], v[152:153], v[64:65], v[10:11] op_sel_hi:[0,1,1]
	v_pk_fma_f32 v[8:9], v[152:153], v[66:67], v[8:9] op_sel_hi:[0,1,1]
	v_fmac_f32_e32 v22, v152, v127
	s_waitcnt vmcnt(42)
	v_pk_fma_f32 v[10:11], v[152:153], v[68:69], v[10:11] op_sel:[1,0,0] op_sel_hi:[1,1,1]
	v_pk_fma_f32 v[8:9], v[152:153], v[84:85], v[8:9] op_sel:[1,0,0] op_sel_hi:[1,1,1]
	v_fmac_f32_e32 v22, v153, v128
	s_waitcnt vmcnt(41)
	v_pk_fma_f32 v[10:11], v[154:155], v[86:87], v[10:11] op_sel_hi:[0,1,1]
	v_pk_fma_f32 v[8:9], v[154:155], v[88:89], v[8:9] op_sel_hi:[0,1,1]
	v_fmac_f32_e32 v22, v154, v129
	s_waitcnt vmcnt(40)
	v_pk_fma_f32 v[10:11], v[154:155], v[90:91], v[10:11] op_sel:[1,0,0] op_sel_hi:[1,1,1]
	v_pk_fma_f32 v[8:9], v[154:155], v[92:93], v[8:9] op_sel:[1,0,0] op_sel_hi:[1,1,1]
	v_fmac_f32_e32 v22, v155, v130
	s_waitcnt vmcnt(39)
	v_pk_fma_f32 v[10:11], v[156:157], v[94:95], v[10:11] op_sel_hi:[0,1,1]
	v_pk_fma_f32 v[8:9], v[156:157], v[96:97], v[8:9] op_sel_hi:[0,1,1]
	v_fmac_f32_e32 v22, v156, v131
	s_waitcnt vmcnt(38)
	v_pk_fma_f32 v[10:11], v[156:157], v[98:99], v[10:11] op_sel:[1,0,0] op_sel_hi:[1,1,1]
	v_pk_fma_f32 v[8:9], v[156:157], v[100:101], v[8:9] op_sel:[1,0,0] op_sel_hi:[1,1,1]
	v_fmac_f32_e32 v22, v157, v15
	ds_bpermute_b32 v29, v27, v23
	ds_bpermute_b32 v30, v27, v24
	ds_bpermute_b32 v31, v27, v25
	ds_bpermute_b32 v123, v27, v26
	s_waitcnt vmcnt(37)
	v_pk_fma_f32 v[10:11], v[158:159], v[102:103], v[10:11] op_sel_hi:[0,1,1]
	v_pk_fma_f32 v[8:9], v[158:159], v[104:105], v[8:9] op_sel_hi:[0,1,1]
	v_fmac_f32_e32 v22, v158, v39
	s_waitcnt vmcnt(36)
	v_pk_fma_f32 v[10:11], v[158:159], v[106:107], v[10:11] op_sel:[1,0,0] op_sel_hi:[1,1,1]
	s_waitcnt lgkmcnt(14)
	v_pk_fma_f32 v[8:9], v[158:159], v[108:109], v[8:9] op_sel:[1,0,0] op_sel_hi:[1,1,1]
	v_fmac_f32_e32 v22, v159, v45
	s_waitcnt vmcnt(35)
	v_pk_fma_f32 v[10:11], v[160:161], v[110:111], v[10:11] op_sel_hi:[0,1,1]
	s_waitcnt lgkmcnt(13)
	v_pk_fma_f32 v[8:9], v[160:161], v[112:113], v[8:9] op_sel_hi:[0,1,1]
	v_fmac_f32_e32 v22, v160, v51
	s_waitcnt vmcnt(34) lgkmcnt(11)
	v_pk_fma_f32 v[10:11], v[160:161], v[114:115], v[10:11] op_sel:[1,0,0] op_sel_hi:[1,1,1]
	s_waitcnt lgkmcnt(9)
	v_pk_fma_f32 v[8:9], v[160:161], v[116:117], v[8:9] op_sel:[1,0,0] op_sel_hi:[1,1,1]
	v_fmac_f32_e32 v22, v161, v57
	s_waitcnt vmcnt(33) lgkmcnt(7)
	v_pk_fma_f32 v[10:11], v[162:163], v[118:119], v[10:11] op_sel_hi:[0,1,1]
	s_waitcnt lgkmcnt(5)
	v_pk_fma_f32 v[8:9], v[162:163], v[120:121], v[8:9] op_sel_hi:[0,1,1]
	v_fmac_f32_e32 v22, v162, v59
	v_add_u32_e32 v27, 64, v27
	s_waitcnt vmcnt(32) lgkmcnt(3)
	v_pk_fma_f32 v[10:11], v[162:163], v[28:29], v[10:11] op_sel:[1,0,0] op_sel_hi:[1,1,1]
	s_waitcnt lgkmcnt(1)
	v_pk_fma_f32 v[8:9], v[162:163], v[30:31], v[8:9] op_sel:[1,0,0] op_sel_hi:[1,1,1]
	s_waitcnt lgkmcnt(0)
	v_fmac_f32_e32 v22, v163, v123
	v_subrev_u32_e32 v44, 56, v27
	ds_bpermute_b32 v40, v44, v0
	ds_bpermute_b32 v41, v44, v23
	ds_bpermute_b32 v42, v44, v24
	ds_bpermute_b32 v43, v44, v25
	ds_bpermute_b32 v124, v44, v26
	v_subrev_u32_e32 v50, 52, v27
	ds_bpermute_b32 v46, v50, v0
	ds_bpermute_b32 v47, v50, v23
	ds_bpermute_b32 v48, v50, v24
	ds_bpermute_b32 v49, v50, v25
	ds_bpermute_b32 v125, v50, v26
	v_subrev_u32_e32 v56, 48, v27
	ds_bpermute_b32 v52, v56, v0
	ds_bpermute_b32 v53, v56, v23
	ds_bpermute_b32 v54, v56, v24
	ds_bpermute_b32 v55, v56, v25
	ds_bpermute_b32 v126, v56, v26
	v_subrev_u32_e32 v33, 60, v27
	v_subrev_u32_e32 v106, 20, v27
	ds_bpermute_b32 v34, v33, v0
	ds_bpermute_b32 v35, v33, v23
	ds_bpermute_b32 v36, v33, v24
	ds_bpermute_b32 v37, v33, v25
	ds_bpermute_b32 v33, v33, v26
	v_add_u32_e32 v110, -16, v27
	v_add_u32_e32 v114, -12, v27
	v_subrev_u32_e32 v68, 44, v27
	v_add_u32_e32 v118, -8, v27
	ds_bpermute_b32 v39, v106, v26
	ds_bpermute_b32 v45, v110, v26
	ds_bpermute_b32 v51, v114, v26
	v_subrev_u32_e32 v86, 40, v27
	v_add_u32_e32 v122, -4, v27
	ds_bpermute_b32 v64, v68, v0
	ds_bpermute_b32 v65, v68, v23
	ds_bpermute_b32 v66, v68, v24
	ds_bpermute_b32 v67, v68, v25
	ds_bpermute_b32 v127, v68, v26
	ds_bpermute_b32 v57, v118, v26
	v_subrev_u32_e32 v90, 36, v27
	ds_bpermute_b32 v68, v86, v0
	ds_bpermute_b32 v69, v86, v23
	ds_bpermute_b32 v84, v86, v24
	ds_bpermute_b32 v85, v86, v25
	ds_bpermute_b32 v128, v86, v26
	ds_bpermute_b32 v59, v122, v26
	v_subrev_u32_e32 v94, 32, v27
	ds_bpermute_b32 v86, v90, v0
	ds_bpermute_b32 v87, v90, v23
	s_waitcnt vmcnt(31) lgkmcnt(14)
	v_pk_fma_f32 v[10:11], v[164:165], v[34:35], v[10:11] op_sel_hi:[0,1,1]
	v_pk_fma_f32 v[8:9], v[164:165], v[36:37], v[8:9] op_sel_hi:[0,1,1]
	v_fmac_f32_e32 v22, v164, v33
	ds_bpermute_b32 v88, v90, v24
	ds_bpermute_b32 v89, v90, v25
	ds_bpermute_b32 v129, v90, v26
	v_subrev_u32_e32 v98, 28, v27
	ds_bpermute_b32 v90, v94, v0
	ds_bpermute_b32 v91, v94, v23
	ds_bpermute_b32 v92, v94, v24
	ds_bpermute_b32 v93, v94, v25
	ds_bpermute_b32 v130, v94, v26
	v_subrev_u32_e32 v102, 24, v27
	ds_bpermute_b32 v94, v98, v0
	ds_bpermute_b32 v95, v98, v23
	ds_bpermute_b32 v96, v98, v24
	ds_bpermute_b32 v97, v98, v25
	ds_bpermute_b32 v131, v98, v26
	ds_bpermute_b32 v98, v102, v0
	ds_bpermute_b32 v99, v102, v23
	ds_bpermute_b32 v100, v102, v24
	ds_bpermute_b32 v101, v102, v25
	ds_bpermute_b32 v15, v102, v26
	ds_bpermute_b32 v102, v106, v0
	ds_bpermute_b32 v103, v106, v23
	ds_bpermute_b32 v104, v106, v24
	ds_bpermute_b32 v105, v106, v25
	ds_bpermute_b32 v106, v110, v0
	ds_bpermute_b32 v107, v110, v23
	ds_bpermute_b32 v108, v110, v24
	ds_bpermute_b32 v109, v110, v25
	ds_bpermute_b32 v110, v114, v0
	ds_bpermute_b32 v111, v114, v23
	ds_bpermute_b32 v112, v114, v24
	ds_bpermute_b32 v113, v114, v25
	ds_bpermute_b32 v114, v118, v0
	ds_bpermute_b32 v115, v118, v23
	ds_bpermute_b32 v116, v118, v24
	ds_bpermute_b32 v117, v118, v25
	ds_bpermute_b32 v118, v122, v0
	ds_bpermute_b32 v119, v122, v23
	ds_bpermute_b32 v120, v122, v24
	ds_bpermute_b32 v121, v122, v25
	ds_bpermute_b32 v28, v27, v0
	s_waitcnt vmcnt(30)
	v_pk_fma_f32 v[10:11], v[164:165], v[40:41], v[10:11] op_sel:[1,0,0] op_sel_hi:[1,1,1]
	v_pk_fma_f32 v[8:9], v[164:165], v[42:43], v[8:9] op_sel:[1,0,0] op_sel_hi:[1,1,1]
	v_fmac_f32_e32 v22, v165, v124
	s_waitcnt vmcnt(29)
	v_pk_fma_f32 v[10:11], v[166:167], v[46:47], v[10:11] op_sel_hi:[0,1,1]
	v_pk_fma_f32 v[8:9], v[166:167], v[48:49], v[8:9] op_sel_hi:[0,1,1]
	v_fmac_f32_e32 v22, v166, v125
	s_waitcnt vmcnt(28)
	v_pk_fma_f32 v[10:11], v[166:167], v[52:53], v[10:11] op_sel:[1,0,0] op_sel_hi:[1,1,1]
	v_pk_fma_f32 v[8:9], v[166:167], v[54:55], v[8:9] op_sel:[1,0,0] op_sel_hi:[1,1,1]
	v_fmac_f32_e32 v22, v167, v126
	s_waitcnt vmcnt(27) lgkmcnt(14)
	v_pk_fma_f32 v[10:11], v[168:169], v[64:65], v[10:11] op_sel_hi:[0,1,1]
	v_pk_fma_f32 v[8:9], v[168:169], v[66:67], v[8:9] op_sel_hi:[0,1,1]
	v_fmac_f32_e32 v22, v168, v127
	s_waitcnt vmcnt(26)
	v_pk_fma_f32 v[10:11], v[168:169], v[68:69], v[10:11] op_sel:[1,0,0] op_sel_hi:[1,1,1]
	v_pk_fma_f32 v[8:9], v[168:169], v[84:85], v[8:9] op_sel:[1,0,0] op_sel_hi:[1,1,1]
	v_fmac_f32_e32 v22, v169, v128
	s_waitcnt vmcnt(25)
	v_pk_fma_f32 v[10:11], v[170:171], v[86:87], v[10:11] op_sel_hi:[0,1,1]
	v_pk_fma_f32 v[8:9], v[170:171], v[88:89], v[8:9] op_sel_hi:[0,1,1]
	v_fmac_f32_e32 v22, v170, v129
	s_waitcnt vmcnt(24)
	v_pk_fma_f32 v[10:11], v[170:171], v[90:91], v[10:11] op_sel:[1,0,0] op_sel_hi:[1,1,1]
	v_pk_fma_f32 v[8:9], v[170:171], v[92:93], v[8:9] op_sel:[1,0,0] op_sel_hi:[1,1,1]
	v_fmac_f32_e32 v22, v171, v130
	s_waitcnt vmcnt(23)
	v_pk_fma_f32 v[10:11], v[172:173], v[94:95], v[10:11] op_sel_hi:[0,1,1]
	v_pk_fma_f32 v[8:9], v[172:173], v[96:97], v[8:9] op_sel_hi:[0,1,1]
	v_fmac_f32_e32 v22, v172, v131
	s_waitcnt vmcnt(22)
	v_pk_fma_f32 v[10:11], v[172:173], v[98:99], v[10:11] op_sel:[1,0,0] op_sel_hi:[1,1,1]
	v_pk_fma_f32 v[8:9], v[172:173], v[100:101], v[8:9] op_sel:[1,0,0] op_sel_hi:[1,1,1]
	v_fmac_f32_e32 v22, v173, v15
	ds_bpermute_b32 v29, v27, v23
	ds_bpermute_b32 v30, v27, v24
	ds_bpermute_b32 v31, v27, v25
	ds_bpermute_b32 v123, v27, v26
	s_waitcnt vmcnt(21)
	v_pk_fma_f32 v[10:11], v[174:175], v[102:103], v[10:11] op_sel_hi:[0,1,1]
	v_pk_fma_f32 v[8:9], v[174:175], v[104:105], v[8:9] op_sel_hi:[0,1,1]
	v_fmac_f32_e32 v22, v174, v39
	s_waitcnt vmcnt(20)
	v_pk_fma_f32 v[10:11], v[174:175], v[106:107], v[10:11] op_sel:[1,0,0] op_sel_hi:[1,1,1]
	s_waitcnt lgkmcnt(14)
	v_pk_fma_f32 v[8:9], v[174:175], v[108:109], v[8:9] op_sel:[1,0,0] op_sel_hi:[1,1,1]
	v_fmac_f32_e32 v22, v175, v45
	s_waitcnt vmcnt(19)
	v_pk_fma_f32 v[10:11], v[176:177], v[110:111], v[10:11] op_sel_hi:[0,1,1]
	s_waitcnt lgkmcnt(13)
	v_pk_fma_f32 v[8:9], v[176:177], v[112:113], v[8:9] op_sel_hi:[0,1,1]
	v_fmac_f32_e32 v22, v176, v51
	s_waitcnt vmcnt(18) lgkmcnt(11)
	v_pk_fma_f32 v[10:11], v[176:177], v[114:115], v[10:11] op_sel:[1,0,0] op_sel_hi:[1,1,1]
	s_waitcnt lgkmcnt(9)
	v_pk_fma_f32 v[8:9], v[176:177], v[116:117], v[8:9] op_sel:[1,0,0] op_sel_hi:[1,1,1]
	v_fmac_f32_e32 v22, v177, v57
	s_waitcnt vmcnt(17) lgkmcnt(7)
	v_pk_fma_f32 v[10:11], v[178:179], v[118:119], v[10:11] op_sel_hi:[0,1,1]
	s_waitcnt lgkmcnt(5)
	v_pk_fma_f32 v[8:9], v[178:179], v[120:121], v[8:9] op_sel_hi:[0,1,1]
	v_fmac_f32_e32 v22, v178, v59
	v_add_u32_e32 v27, 64, v27
	s_waitcnt vmcnt(16) lgkmcnt(3)
	v_pk_fma_f32 v[10:11], v[178:179], v[28:29], v[10:11] op_sel:[1,0,0] op_sel_hi:[1,1,1]
	s_waitcnt lgkmcnt(1)
	v_pk_fma_f32 v[8:9], v[178:179], v[30:31], v[8:9] op_sel:[1,0,0] op_sel_hi:[1,1,1]
	s_waitcnt lgkmcnt(0)
	v_fmac_f32_e32 v22, v179, v123
	v_subrev_u32_e32 v44, 56, v27
	ds_bpermute_b32 v40, v44, v0
	ds_bpermute_b32 v41, v44, v23
	ds_bpermute_b32 v42, v44, v24
	ds_bpermute_b32 v43, v44, v25
	ds_bpermute_b32 v124, v44, v26
	v_subrev_u32_e32 v50, 52, v27
	ds_bpermute_b32 v46, v50, v0
	ds_bpermute_b32 v47, v50, v23
	ds_bpermute_b32 v48, v50, v24
	ds_bpermute_b32 v49, v50, v25
	ds_bpermute_b32 v125, v50, v26
	v_subrev_u32_e32 v56, 48, v27
	ds_bpermute_b32 v52, v56, v0
	ds_bpermute_b32 v53, v56, v23
	ds_bpermute_b32 v54, v56, v24
	ds_bpermute_b32 v55, v56, v25
	ds_bpermute_b32 v126, v56, v26
	v_subrev_u32_e32 v33, 60, v27
	v_subrev_u32_e32 v106, 20, v27
	ds_bpermute_b32 v34, v33, v0
	ds_bpermute_b32 v35, v33, v23
	ds_bpermute_b32 v36, v33, v24
	ds_bpermute_b32 v37, v33, v25
	ds_bpermute_b32 v33, v33, v26
	v_add_u32_e32 v110, -16, v27
	v_add_u32_e32 v114, -12, v27
	v_subrev_u32_e32 v68, 44, v27
	v_add_u32_e32 v118, -8, v27
	ds_bpermute_b32 v39, v106, v26
	ds_bpermute_b32 v45, v110, v26
	ds_bpermute_b32 v51, v114, v26
	v_subrev_u32_e32 v86, 40, v27
	v_add_u32_e32 v122, -4, v27
	ds_bpermute_b32 v64, v68, v0
	ds_bpermute_b32 v65, v68, v23
	ds_bpermute_b32 v66, v68, v24
	ds_bpermute_b32 v67, v68, v25
	ds_bpermute_b32 v127, v68, v26
	ds_bpermute_b32 v57, v118, v26
	v_subrev_u32_e32 v90, 36, v27
	ds_bpermute_b32 v68, v86, v0
	ds_bpermute_b32 v69, v86, v23
	ds_bpermute_b32 v84, v86, v24
	ds_bpermute_b32 v85, v86, v25
	ds_bpermute_b32 v128, v86, v26
	ds_bpermute_b32 v59, v122, v26
	v_subrev_u32_e32 v94, 32, v27
	ds_bpermute_b32 v86, v90, v0
	ds_bpermute_b32 v87, v90, v23
	s_waitcnt vmcnt(15) lgkmcnt(14)
	v_pk_fma_f32 v[10:11], v[180:181], v[34:35], v[10:11] op_sel_hi:[0,1,1]
	v_pk_fma_f32 v[8:9], v[180:181], v[36:37], v[8:9] op_sel_hi:[0,1,1]
	v_fmac_f32_e32 v22, v180, v33
	ds_bpermute_b32 v88, v90, v24
	ds_bpermute_b32 v89, v90, v25
	ds_bpermute_b32 v129, v90, v26
	v_subrev_u32_e32 v98, 28, v27
	ds_bpermute_b32 v90, v94, v0
	ds_bpermute_b32 v91, v94, v23
	ds_bpermute_b32 v92, v94, v24
	ds_bpermute_b32 v93, v94, v25
	ds_bpermute_b32 v130, v94, v26
	v_subrev_u32_e32 v102, 24, v27
	ds_bpermute_b32 v94, v98, v0
	ds_bpermute_b32 v95, v98, v23
	ds_bpermute_b32 v96, v98, v24
	ds_bpermute_b32 v97, v98, v25
	ds_bpermute_b32 v131, v98, v26
	ds_bpermute_b32 v98, v102, v0
	ds_bpermute_b32 v99, v102, v23
	ds_bpermute_b32 v100, v102, v24
	ds_bpermute_b32 v101, v102, v25
	ds_bpermute_b32 v15, v102, v26
	ds_bpermute_b32 v102, v106, v0
	ds_bpermute_b32 v103, v106, v23
	ds_bpermute_b32 v104, v106, v24
	ds_bpermute_b32 v105, v106, v25
	ds_bpermute_b32 v106, v110, v0
	ds_bpermute_b32 v107, v110, v23
	ds_bpermute_b32 v108, v110, v24
	ds_bpermute_b32 v109, v110, v25
	ds_bpermute_b32 v110, v114, v0
	ds_bpermute_b32 v111, v114, v23
	ds_bpermute_b32 v112, v114, v24
	ds_bpermute_b32 v113, v114, v25
	ds_bpermute_b32 v114, v118, v0
	ds_bpermute_b32 v115, v118, v23
	ds_bpermute_b32 v116, v118, v24
	ds_bpermute_b32 v117, v118, v25
	ds_bpermute_b32 v118, v122, v0
	ds_bpermute_b32 v119, v122, v23
	ds_bpermute_b32 v120, v122, v24
	ds_bpermute_b32 v121, v122, v25
	ds_bpermute_b32 v28, v27, v0
	s_waitcnt vmcnt(14)
	v_pk_fma_f32 v[10:11], v[180:181], v[40:41], v[10:11] op_sel:[1,0,0] op_sel_hi:[1,1,1]
	v_pk_fma_f32 v[8:9], v[180:181], v[42:43], v[8:9] op_sel:[1,0,0] op_sel_hi:[1,1,1]
	v_fmac_f32_e32 v22, v181, v124
	s_waitcnt vmcnt(13)
	v_pk_fma_f32 v[10:11], v[182:183], v[46:47], v[10:11] op_sel_hi:[0,1,1]
	v_pk_fma_f32 v[8:9], v[182:183], v[48:49], v[8:9] op_sel_hi:[0,1,1]
	v_fmac_f32_e32 v22, v182, v125
	s_waitcnt vmcnt(12)
	v_pk_fma_f32 v[10:11], v[182:183], v[52:53], v[10:11] op_sel:[1,0,0] op_sel_hi:[1,1,1]
	v_pk_fma_f32 v[8:9], v[182:183], v[54:55], v[8:9] op_sel:[1,0,0] op_sel_hi:[1,1,1]
	v_fmac_f32_e32 v22, v183, v126
	s_waitcnt vmcnt(11) lgkmcnt(14)
	v_pk_fma_f32 v[10:11], v[184:185], v[64:65], v[10:11] op_sel_hi:[0,1,1]
	v_pk_fma_f32 v[8:9], v[184:185], v[66:67], v[8:9] op_sel_hi:[0,1,1]
	v_fmac_f32_e32 v22, v184, v127
	s_waitcnt vmcnt(10)
	v_pk_fma_f32 v[10:11], v[184:185], v[68:69], v[10:11] op_sel:[1,0,0] op_sel_hi:[1,1,1]
	v_pk_fma_f32 v[8:9], v[184:185], v[84:85], v[8:9] op_sel:[1,0,0] op_sel_hi:[1,1,1]
	v_fmac_f32_e32 v22, v185, v128
	s_waitcnt vmcnt(9)
	v_pk_fma_f32 v[10:11], v[186:187], v[86:87], v[10:11] op_sel_hi:[0,1,1]
	v_pk_fma_f32 v[8:9], v[186:187], v[88:89], v[8:9] op_sel_hi:[0,1,1]
	v_fmac_f32_e32 v22, v186, v129
	s_waitcnt vmcnt(8)
	v_pk_fma_f32 v[10:11], v[186:187], v[90:91], v[10:11] op_sel:[1,0,0] op_sel_hi:[1,1,1]
	v_pk_fma_f32 v[8:9], v[186:187], v[92:93], v[8:9] op_sel:[1,0,0] op_sel_hi:[1,1,1]
	v_fmac_f32_e32 v22, v187, v130
	s_waitcnt vmcnt(7)
	v_pk_fma_f32 v[10:11], v[188:189], v[94:95], v[10:11] op_sel_hi:[0,1,1]
	v_pk_fma_f32 v[8:9], v[188:189], v[96:97], v[8:9] op_sel_hi:[0,1,1]
	v_fmac_f32_e32 v22, v188, v131
	s_waitcnt vmcnt(6)
	v_pk_fma_f32 v[10:11], v[188:189], v[98:99], v[10:11] op_sel:[1,0,0] op_sel_hi:[1,1,1]
	v_pk_fma_f32 v[8:9], v[188:189], v[100:101], v[8:9] op_sel:[1,0,0] op_sel_hi:[1,1,1]
	v_fmac_f32_e32 v22, v189, v15
	ds_bpermute_b32 v29, v27, v23
	ds_bpermute_b32 v30, v27, v24
	ds_bpermute_b32 v31, v27, v25
	ds_bpermute_b32 v123, v27, v26
	s_waitcnt vmcnt(5)
	v_pk_fma_f32 v[10:11], v[190:191], v[102:103], v[10:11] op_sel_hi:[0,1,1]
	v_pk_fma_f32 v[8:9], v[190:191], v[104:105], v[8:9] op_sel_hi:[0,1,1]
	v_fmac_f32_e32 v22, v190, v39
	s_waitcnt vmcnt(4)
	v_pk_fma_f32 v[10:11], v[190:191], v[106:107], v[10:11] op_sel:[1,0,0] op_sel_hi:[1,1,1]
	s_waitcnt lgkmcnt(14)
	v_pk_fma_f32 v[8:9], v[190:191], v[108:109], v[8:9] op_sel:[1,0,0] op_sel_hi:[1,1,1]
	v_fmac_f32_e32 v22, v191, v45
	s_waitcnt vmcnt(3)
	v_pk_fma_f32 v[10:11], v[192:193], v[110:111], v[10:11] op_sel_hi:[0,1,1]
	s_waitcnt lgkmcnt(13)
	v_pk_fma_f32 v[8:9], v[192:193], v[112:113], v[8:9] op_sel_hi:[0,1,1]
	v_fmac_f32_e32 v22, v192, v51
	s_waitcnt vmcnt(2) lgkmcnt(11)
	v_pk_fma_f32 v[10:11], v[192:193], v[114:115], v[10:11] op_sel:[1,0,0] op_sel_hi:[1,1,1]
	s_waitcnt lgkmcnt(9)
	v_pk_fma_f32 v[8:9], v[192:193], v[116:117], v[8:9] op_sel:[1,0,0] op_sel_hi:[1,1,1]
	v_fmac_f32_e32 v22, v193, v57
	s_waitcnt vmcnt(1) lgkmcnt(7)
	v_pk_fma_f32 v[10:11], v[194:195], v[118:119], v[10:11] op_sel_hi:[0,1,1]
	s_waitcnt lgkmcnt(5)
	v_pk_fma_f32 v[8:9], v[194:195], v[120:121], v[8:9] op_sel_hi:[0,1,1]
	v_fmac_f32_e32 v22, v194, v59
	v_add_u32_e32 v27, 64, v27
	s_waitcnt vmcnt(0) lgkmcnt(3)
	v_pk_fma_f32 v[10:11], v[194:195], v[28:29], v[10:11] op_sel:[1,0,0] op_sel_hi:[1,1,1]
	s_waitcnt lgkmcnt(1)
	v_pk_fma_f32 v[8:9], v[194:195], v[30:31], v[8:9] op_sel:[1,0,0] op_sel_hi:[1,1,1]
	s_waitcnt lgkmcnt(0)
	v_fmac_f32_e32 v22, v195, v123
	s_mov_b32 s70, 64
	s_mov_b64 s[8:9], 0
	s_and_b64 vcc, exec, s[6:7]
	s_cbranch_vccz .LBB0_20
	v_lshlrev_b32_e32 v0, 3, v17
	v_and_b32_e32 v6, 0xffffffc0, v0
	v_ashrrev_i32_e32 v7, 31, v6
	v_lshl_add_u64 v[6:7], v[6:7], 2, v[2:3]
	v_add_co_u32_e32 v12, vcc, 0x3000, v6
	global_store_dword v[6:7], v10, off
	s_nop 0
	v_addc_co_u32_e32 v13, vcc, 0, v7, vcc
	v_add_co_u32_e32 v10, vcc, 0x6000, v6
	global_store_dword v[12:13], v11, off
	s_nop 0
	v_addc_co_u32_e32 v11, vcc, 0, v7, vcc
	global_store_dword v[10:11], v8, off
	v_add_co_u32_e32 v10, vcc, 0x9000, v6
	v_add_u32_e32 v17, s33, v17
	s_nop 0
	v_addc_co_u32_e32 v11, vcc, 0, v7, vcc
	v_add_co_u32_e32 v6, vcc, 0xc000, v6
	v_add_u32_e32 v19, s3, v19
	s_nop 0
	v_addc_co_u32_e32 v7, vcc, 0, v7, vcc
	v_cmp_lt_i32_e32 vcc, s69, v17
	s_or_b64 s[4:5], vcc, s[4:5]
	global_store_dword v[10:11], v9, off
	global_store_dword v[6:7], v22, off
	s_andn2_b64 exec, exec, s[4:5]
	s_cbranch_execnz .LBB0_19
